# P1: first two vmcnt waits of each tile's first K-iteration relaxed by the proven minimum of 16 epilogue memory ops (every EpiA variant block issues >=16), prologue drained once
# speedup vs baseline: 1.0024x; 1.0024x over previous
.LBB0_260:
	v_bfe_u32 v203, v202, 4, 2
	v_and_b32_e32 v151, 15, v202
	v_lshlrev_b32_e32 v148, 4, v203
	v_lshlrev_b32_e32 v13, 2, v202
	v_readlane_b32 s33, v246, 0
	s_and_b32 s50, s5, 3
	v_lshl_or_b32 v12, v151, 6, v148
	s_lshl_b32 s5, s6, 13
	v_and_b32_e32 v13, 32, v13
	s_add_i32 s11, s33, 0x18000
	v_bitop3_b32 v12, v12, s5, v13 bitop3:0xde
	v_lshlrev_b32_e32 v14, 6, v202
	s_movk_i32 s5, 0x3c0
	s_add_i32 s51, s11, s4
	s_mov_b64 s[18:19], 0x80
	s_lshl_b32 s60, s6, 6
	v_and_or_b32 v14, v14, s5, v148
	s_lshl_b32 s5, s50, 12
	v_lshl_add_u64 v[6:7], v[6:7], 0, s[18:19]
	s_mov_b32 m0, s51
	s_add_i32 s52, s51, 0x2000
	s_add_i32 s54, s44, 0x8000
	s_add_i32 s55, s44, 0xa000
	global_load_lds_dwordx4 v[6:7], off
	v_lshl_add_u64 v[4:5], v[4:5], 0, s[18:19]
	s_mov_b32 m0, s52
	s_add_u32 s6, s16, 0x40080
	global_load_lds_dwordx4 v[4:5], off
	v_lshl_add_u64 v[2:3], v[2:3], 0, s[18:19]
	s_mov_b32 m0, s54
	s_addc_u32 s7, s17, 0
	s_add_i32 s15, s33, 0x1c000
	global_load_lds_dwordx4 v[2:3], off
	v_lshl_add_u64 v[0:1], v[0:1], 0, s[18:19]
	s_mov_b32 m0, s55
	s_add_i32 s56, s15, s4
	global_load_lds_dwordx4 v[0:1], off
	v_lshl_add_u64 v[0:1], s[6:7], 0, v[144:145]
	s_mov_b32 m0, s56
	s_add_i32 s57, s56, 0x2000
	global_load_lds_dwordx4 v[0:1], off
	v_lshl_add_u64 v[0:1], s[6:7], 0, v[146:147]
	s_mov_b32 m0, s57
	v_readlane_b32 s6, v246, 1
	global_load_lds_dwordx4 v[0:1], off
	s_waitcnt vmcnt(8)
	s_barrier
	v_sub_co_u32_e64 v0, s[24:25], s50, 2
	s_nop 0
	v_readfirstlane_b32 s4, v0
	s_lshl_b32 s4, s4, 6
	v_or_b32_e32 v204, s60, v151
	v_bitop3_b32 v13, s5, v14, v13 bitop3:0xf6
	s_lshl_b32 s58, s50, 6
	s_ashr_i32 s5, s4, 31
	s_addk_i32 s60, 0x80
	s_ashr_i32 s61, s6, 31
	s_ashr_i32 s63, s30, 31
	s_add_u32 s26, s22, 0x192cc000
	s_addc_u32 s27, s23, 0
	s_lshl_b64 s[4:5], s[4:5], 1
	s_add_u32 s4, s22, s4
	v_and_b32_e32 v2, 7, v202
	v_ashrrev_i32_e32 v1, 31, v0
	s_addc_u32 s5, s23, s5
	v_or_b32_e32 v208, 0x4000, v2
	v_lshlrev_b64 v[0:1], 8, v[0:1]
	v_or_b32_e32 v209, 0xfff80000, v2
	v_lshl_add_u64 v[2:3], s[4:5], 0, v[148:149]
	s_mov_b64 s[4:5], 0x8d64000
	v_lshl_add_u64 v[152:153], v[2:3], 0, s[4:5]
	v_lshl_add_u64 v[0:1], s[20:21], 0, v[0:1]
	s_mov_b64 s[4:5], 0x9600000
	v_lshl_add_u64 v[154:155], v[0:1], 0, s[4:5]
	s_mov_b64 s[4:5], 0x8480000
	v_lshl_add_u64 v[156:157], v[0:1], 0, s[4:5]
	s_lshl_b32 s4, s50, 7
	s_add_u32 s4, s22, s4
	s_addc_u32 s5, s23, 0
	v_lshl_add_u64 v[0:1], s[4:5], 0, v[148:149]
	s_mov_b64 s[4:5], 0x8524000
	v_lshl_add_u64 v[158:159], v[0:1], 0, s[4:5]
	v_lshl_add_u64 v[0:1], s[22:23], 0, v[148:149]
	s_mov_b64 s[4:5], 0x6424000
	v_lshl_add_u64 v[160:161], v[0:1], 0, s[4:5]
	v_lshlrev_b32_e32 v0, 8, v202
	s_lshl_b32 s4, s50, 8
	v_and_b32_e32 v0, 0xffff8000, v0
	v_lshlrev_b32_e32 v1, 11, v10
	s_add_u32 s4, s20, s4
	v_or3_b32 v0, v8, v0, v1
	s_addc_u32 s5, s21, 0
	v_add_u32_e32 v162, v0, v9
	v_lshlrev_b32_e32 v0, 4, v11
	s_add_u32 s28, s4, 0x8e00000
	v_and_b32_e32 v0, 0xffff8000, v0
	s_waitcnt vmcnt(6)
	s_addc_u32 s29, s5, 0
	v_or3_b32 v0, v8, v0, v1
	v_lshlrev_b32_e32 v150, 3, v203
	s_add_u32 s30, s4, 0x8400000
	v_add_u32_e32 v164, v0, v9
	v_mbcnt_lo_u32_b32 v0, -1, 0
	s_mov_b32 s53, 0x8000
	v_or_b32_e32 v205, 16, v204
	v_or_b32_e32 v206, 32, v204
	v_or_b32_e32 v207, 48, v204
	s_mov_b32 s59, 0
	s_mov_b32 s62, s6
	s_addc_u32 s31, s5, 0
	v_or_b32_e32 v210, s58, v150
	v_mov_b32_e32 v163, v149
	v_mov_b32_e32 v165, v149
	v_mov_b64_e32 v[166:167], 0x5ab
	v_add_u32_e32 v211, s2, v13
	v_add_u32_e32 v212, s33, v12
	v_add_u32_e32 v213, s3, v13
	v_add_u32_e32 v214, s11, v13
	v_add_u32_e32 v215, s15, v13
	s_movk_i32 s64, 0xfdf
	s_movk_i32 s65, 0xfef
	s_movk_i32 s66, 0xfff
	v_mov_b32_e32 v216, 0x358637bd
	v_mov_b32_e32 v217, 0x3e000000
	v_mov_b32_e32 v218, 0x78
	v_mbcnt_hi_u32_b32 v219, -1, v0
	v_mov_b32_e32 v220, 0xfcf
	s_barrier
	v_readlane_b32 s7, v246, 2
	s_waitcnt vmcnt(0)
	s_branch .LBB0_262

.LBB0_273:
	s_xor_b64 s[34:35], s[6:7], -1
	s_and_b64 s[6:7], s[6:7], exec
	s_cselect_b32 s11, s13, s3
	s_cselect_b32 s15, s12, s2
	s_cselect_b32 s36, s17, s5
	s_cselect_b32 s37, s16, s4
	s_add_u32 s2, s2, 0x40080
	s_addc_u32 s3, s3, 0
	s_add_u32 s38, s4, 0x100
	s_addc_u32 s39, s5, 0
	s_mov_b32 s69, -2
	s_waitcnt lgkmcnt(0)
	ds_read_b128 v[128:131], v211
	ds_read_b128 v[132:135], v211 offset:1024
	ds_read_b128 v[136:139], v211 offset:2048
	ds_read_b128 v[140:143], v211 offset:3072
	s_add_u32 s4, s2, 0xfffc0080
	s_addc_u32 s5, s3, -1
	s_cmp_eq_u32 s69, 12
	s_cselect_b32 s7, s11, s5
	s_cselect_b32 s6, s15, s4
	s_cselect_b32 s5, s36, s39
	s_cselect_b32 s4, s37, s38
	v_lshl_add_u64 v[200:201], s[2:3], 0, v[162:163]
	s_add_i32 m0, s44, 0xc000
	ds_read_b128 v[168:171], v212
	ds_read_b128 v[172:175], v212 offset:1024
	ds_read_b128 v[176:179], v212 offset:2048
	ds_read_b128 v[180:183], v212 offset:3072
	ds_read_b128 v[184:187], v212 offset:4096
	ds_read_b128 v[188:191], v212 offset:5120
	ds_read_b128 v[192:195], v212 offset:6144
	ds_read_b128 v[196:199], v212 offset:7168
	global_load_lds_dwordx4 v[200:201], off
	v_lshl_add_u64 v[200:201], s[2:3], 0, v[164:165]
	s_add_i32 m0, s44, 0xe000
	s_nop 0
	global_load_lds_dwordx4 v[200:201], off
	ds_read_b128 v[222:225], v213
	ds_read_b128 v[226:229], v213 offset:1024
	ds_read_b128 v[230:233], v213 offset:2048
	ds_read_b128 v[234:237], v213 offset:3072
	s_waitcnt lgkmcnt(0)
	s_waitcnt vmcnt(24)
	s_barrier
	s_setprio 1
	v_mfma_f32_16x16x32_bf16 v[124:127], v[128:131], v[168:171], 0
	v_mfma_f32_16x16x32_bf16 v[120:123], v[136:139], v[168:171], 0
	v_mfma_f32_16x16x32_bf16 v[108:111], v[128:131], v[176:179], 0
	v_mfma_f32_16x16x32_bf16 v[104:107], v[136:139], v[176:179], 0
	v_mfma_f32_16x16x32_bf16 v[92:95], v[128:131], v[184:187], 0
	v_mfma_f32_16x16x32_bf16 v[88:91], v[136:139], v[184:187], 0
	v_mfma_f32_16x16x32_bf16 v[76:79], v[128:131], v[192:195], 0
	v_mfma_f32_16x16x32_bf16 v[72:75], v[136:139], v[192:195], 0
	v_mfma_f32_16x16x32_bf16 v[124:127], v[132:135], v[172:175], v[124:127]
	v_mfma_f32_16x16x32_bf16 v[120:123], v[140:143], v[172:175], v[120:123]
	v_mfma_f32_16x16x32_bf16 v[108:111], v[132:135], v[180:183], v[108:111]
	v_mfma_f32_16x16x32_bf16 v[104:107], v[140:143], v[180:183], v[104:107]
	v_mfma_f32_16x16x32_bf16 v[92:95], v[132:135], v[188:191], v[92:95]
	v_mfma_f32_16x16x32_bf16 v[88:91], v[140:143], v[188:191], v[88:91]
	v_mfma_f32_16x16x32_bf16 v[76:79], v[132:135], v[196:199], v[76:79]
	v_mfma_f32_16x16x32_bf16 v[72:75], v[140:143], v[196:199], v[72:75]
	v_mfma_f32_16x16x32_bf16 v[116:119], v[222:225], v[168:171], 0
	v_mfma_f32_16x16x32_bf16 v[112:115], v[230:233], v[168:171], 0
	v_mfma_f32_16x16x32_bf16 v[100:103], v[222:225], v[176:179], 0
	v_mfma_f32_16x16x32_bf16 v[96:99], v[230:233], v[176:179], 0
	v_mfma_f32_16x16x32_bf16 v[84:87], v[222:225], v[184:187], 0
	v_mfma_f32_16x16x32_bf16 v[80:83], v[230:233], v[184:187], 0
	v_mfma_f32_16x16x32_bf16 v[68:71], v[222:225], v[192:195], 0
	v_mfma_f32_16x16x32_bf16 v[64:67], v[230:233], v[192:195], 0
	v_mfma_f32_16x16x32_bf16 v[116:119], v[226:229], v[172:175], v[116:119]
	v_mfma_f32_16x16x32_bf16 v[112:115], v[234:237], v[172:175], v[112:115]
	v_mfma_f32_16x16x32_bf16 v[100:103], v[226:229], v[180:183], v[100:103]
	v_mfma_f32_16x16x32_bf16 v[96:99], v[234:237], v[180:183], v[96:99]
	v_mfma_f32_16x16x32_bf16 v[84:87], v[226:229], v[188:191], v[84:87]
	v_mfma_f32_16x16x32_bf16 v[80:83], v[234:237], v[188:191], v[80:83]
	v_mfma_f32_16x16x32_bf16 v[68:71], v[226:229], v[196:199], v[68:71]
	v_mfma_f32_16x16x32_bf16 v[64:67], v[234:237], v[196:199], v[64:67]
	s_setprio 0
	s_barrier
	s_lshl_b32 s84, s67, 10
	s_cmp_eq_u32 s68, 0
	s_mov_b32 s85, 0x6200000
	s_cselect_b32 s85, s85, 0x6221000
	s_add_u32 s86, s22, s85
	s_addc_u32 s87, s23, 0
	s_add_u32 s86, s86, s84
	s_addc_u32 s87, s87, 0
	v_lshlrev_b32_e32 v221, 2, v204
	v_lshlrev_b32_e32 v247, 2, v205
	v_lshlrev_b32_e32 v250, 2, v206
	v_lshlrev_b32_e32 v251, 2, v207
	v_lshlrev_b32_e32 v252, 2, v204
	v_lshlrev_b32_e32 v253, 2, v204
	v_lshlrev_b32_e32 v254, 2, v204
	v_lshlrev_b32_e32 v255, 2, v204
	global_load_dword v221, v221, s[86:87]
	global_load_dword v247, v247, s[86:87]
	global_load_dword v250, v250, s[86:87]
	global_load_dword v251, v251, s[86:87]
	global_load_dword v252, v252, s[86:87] offset:512
	global_load_dword v253, v253, s[86:87] offset:576
	global_load_dword v254, v254, s[86:87] offset:640
	global_load_dword v255, v255, s[86:87] offset:704
	ds_read_b128 v[168:171], v212 offset:16384
	ds_read_b128 v[172:175], v212 offset:17408
	ds_read_b128 v[176:179], v212 offset:18432
	ds_read_b128 v[180:183], v212 offset:19456
	ds_read_b128 v[184:187], v212 offset:20480
	ds_read_b128 v[188:191], v212 offset:21504
	ds_read_b128 v[192:195], v212 offset:22528
	ds_read_b128 v[196:199], v212 offset:23552
	s_mov_b32 m0, s42
	v_lshl_add_u64 v[200:201], s[4:5], 0, v[144:145]
	global_load_lds_dwordx4 v[200:201], off
	v_lshl_add_u64 v[238:239], s[4:5], 0, v[146:147]
	s_mov_b32 m0, s43
	s_nop 0
	global_load_lds_dwordx4 v[238:239], off
	s_mov_b32 m0, s44
	v_lshl_add_u64 v[240:241], s[6:7], 0, v[144:145]
	global_load_lds_dwordx4 v[240:241], off
	v_lshl_add_u64 v[242:243], s[6:7], 0, v[146:147]
	s_mov_b32 m0, s45
	s_nop 0
	global_load_lds_dwordx4 v[242:243], off
	s_add_u32 s70, s4, 0x40000
	s_addc_u32 s71, s5, 0
	s_mov_b32 m0, s46
	v_lshl_add_u64 v[248:249], s[70:71], 0, v[144:145]
	global_load_lds_dwordx4 v[248:249], off
	v_lshl_add_u64 v[248:249], s[70:71], 0, v[146:147]
	s_mov_b32 m0, s47
	s_nop 0
	global_load_lds_dwordx4 v[248:249], off
	s_waitcnt lgkmcnt(0)
	s_waitcnt vmcnt(32)
	s_barrier
	s_setprio 1
	v_mfma_f32_16x16x32_bf16 v[60:63], v[128:131], v[168:171], 0
	v_mfma_f32_16x16x32_bf16 v[56:59], v[136:139], v[168:171], 0
	v_mfma_f32_16x16x32_bf16 v[44:47], v[128:131], v[176:179], 0
	v_mfma_f32_16x16x32_bf16 v[40:43], v[136:139], v[176:179], 0
	v_mfma_f32_16x16x32_bf16 v[28:31], v[128:131], v[184:187], 0
	v_mfma_f32_16x16x32_bf16 v[24:27], v[136:139], v[184:187], 0
	v_mfma_f32_16x16x32_bf16 v[12:15], v[128:131], v[192:195], 0
	v_mfma_f32_16x16x32_bf16 v[8:11], v[136:139], v[192:195], 0
	v_mfma_f32_16x16x32_bf16 v[60:63], v[132:135], v[172:175], v[60:63]
	v_mfma_f32_16x16x32_bf16 v[56:59], v[140:143], v[172:175], v[56:59]
	v_mfma_f32_16x16x32_bf16 v[44:47], v[132:135], v[180:183], v[44:47]
	v_mfma_f32_16x16x32_bf16 v[40:43], v[140:143], v[180:183], v[40:43]
	v_mfma_f32_16x16x32_bf16 v[28:31], v[132:135], v[188:191], v[28:31]
	v_mfma_f32_16x16x32_bf16 v[24:27], v[140:143], v[188:191], v[24:27]
	v_mfma_f32_16x16x32_bf16 v[12:15], v[132:135], v[196:199], v[12:15]
	v_mfma_f32_16x16x32_bf16 v[8:11], v[140:143], v[196:199], v[8:11]
	v_mfma_f32_16x16x32_bf16 v[52:55], v[222:225], v[168:171], 0
	v_mfma_f32_16x16x32_bf16 v[48:51], v[230:233], v[168:171], 0
	v_mfma_f32_16x16x32_bf16 v[36:39], v[222:225], v[176:179], 0
	v_mfma_f32_16x16x32_bf16 v[32:35], v[230:233], v[176:179], 0
	v_mfma_f32_16x16x32_bf16 v[20:23], v[222:225], v[184:187], 0
	v_mfma_f32_16x16x32_bf16 v[16:19], v[230:233], v[184:187], 0
	v_mfma_f32_16x16x32_bf16 v[4:7], v[222:225], v[192:195], 0
	v_mfma_f32_16x16x32_bf16 v[0:3], v[230:233], v[192:195], 0
	v_mfma_f32_16x16x32_bf16 v[52:55], v[226:229], v[172:175], v[52:55]
	v_mfma_f32_16x16x32_bf16 v[48:51], v[234:237], v[172:175], v[48:51]
	v_mfma_f32_16x16x32_bf16 v[36:39], v[226:229], v[180:183], v[36:39]
	v_mfma_f32_16x16x32_bf16 v[32:35], v[234:237], v[180:183], v[32:35]
	v_mfma_f32_16x16x32_bf16 v[20:23], v[226:229], v[188:191], v[20:23]
	v_mfma_f32_16x16x32_bf16 v[16:19], v[234:237], v[188:191], v[16:19]
	v_mfma_f32_16x16x32_bf16 v[4:7], v[226:229], v[196:199], v[4:7]
	v_mfma_f32_16x16x32_bf16 v[0:3], v[234:237], v[196:199], v[0:3]
	s_setprio 0
	s_barrier
	ds_read_b128 v[128:131], v214
	ds_read_b128 v[132:135], v214 offset:1024
	ds_read_b128 v[136:139], v214 offset:2048
	ds_read_b128 v[140:143], v214 offset:3072
	s_add_u32 s6, s6, 0x40000
	s_addc_u32 s7, s7, 0
	s_mov_b32 m0, s48
	v_lshl_add_u64 v[222:223], s[6:7], 0, v[144:145]
	ds_read_b128 v[168:171], v212 offset:32768
	ds_read_b128 v[172:175], v212 offset:33792
	ds_read_b128 v[176:179], v212 offset:34816
	ds_read_b128 v[180:183], v212 offset:35840
	ds_read_b128 v[184:187], v212 offset:36864
	ds_read_b128 v[188:191], v212 offset:37888
	ds_read_b128 v[192:195], v212 offset:38912
	ds_read_b128 v[196:199], v212 offset:39936
	global_load_lds_dwordx4 v[222:223], off
	v_lshl_add_u64 v[222:223], s[6:7], 0, v[146:147]
	s_mov_b32 m0, s49
	s_nop 0
	global_load_lds_dwordx4 v[222:223], off
	ds_read_b128 v[222:225], v215
	ds_read_b128 v[226:229], v215 offset:1024
	ds_read_b128 v[230:233], v215 offset:2048
	ds_read_b128 v[234:237], v215 offset:3072
	s_waitcnt lgkmcnt(0)
	s_waitcnt vmcnt(16)
	s_barrier
	s_setprio 1
	v_mfma_f32_16x16x32_bf16 v[124:127], v[128:131], v[168:171], v[124:127]
	v_mfma_f32_16x16x32_bf16 v[120:123], v[136:139], v[168:171], v[120:123]
	v_mfma_f32_16x16x32_bf16 v[108:111], v[128:131], v[176:179], v[108:111]
	v_mfma_f32_16x16x32_bf16 v[104:107], v[136:139], v[176:179], v[104:107]
	v_mfma_f32_16x16x32_bf16 v[92:95], v[128:131], v[184:187], v[92:95]
	v_mfma_f32_16x16x32_bf16 v[88:91], v[136:139], v[184:187], v[88:91]
	v_mfma_f32_16x16x32_bf16 v[76:79], v[128:131], v[192:195], v[76:79]
	v_mfma_f32_16x16x32_bf16 v[72:75], v[136:139], v[192:195], v[72:75]
	v_mfma_f32_16x16x32_bf16 v[124:127], v[132:135], v[172:175], v[124:127]
	v_mfma_f32_16x16x32_bf16 v[120:123], v[140:143], v[172:175], v[120:123]
	v_mfma_f32_16x16x32_bf16 v[108:111], v[132:135], v[180:183], v[108:111]
	v_mfma_f32_16x16x32_bf16 v[104:107], v[140:143], v[180:183], v[104:107]
	v_mfma_f32_16x16x32_bf16 v[92:95], v[132:135], v[188:191], v[92:95]
	v_mfma_f32_16x16x32_bf16 v[88:91], v[140:143], v[188:191], v[88:91]
	v_mfma_f32_16x16x32_bf16 v[76:79], v[132:135], v[196:199], v[76:79]
	v_mfma_f32_16x16x32_bf16 v[72:75], v[140:143], v[196:199], v[72:75]
	v_mfma_f32_16x16x32_bf16 v[116:119], v[222:225], v[168:171], v[116:119]
	v_mfma_f32_16x16x32_bf16 v[112:115], v[230:233], v[168:171], v[112:115]
	v_mfma_f32_16x16x32_bf16 v[100:103], v[222:225], v[176:179], v[100:103]
	v_mfma_f32_16x16x32_bf16 v[96:99], v[230:233], v[176:179], v[96:99]
	v_mfma_f32_16x16x32_bf16 v[84:87], v[222:225], v[184:187], v[84:87]
	v_mfma_f32_16x16x32_bf16 v[80:83], v[230:233], v[184:187], v[80:83]
	v_mfma_f32_16x16x32_bf16 v[68:71], v[222:225], v[192:195], v[68:71]
	v_mfma_f32_16x16x32_bf16 v[64:67], v[230:233], v[192:195], v[64:67]
	v_mfma_f32_16x16x32_bf16 v[116:119], v[226:229], v[172:175], v[116:119]
	v_mfma_f32_16x16x32_bf16 v[112:115], v[234:237], v[172:175], v[112:115]
	v_mfma_f32_16x16x32_bf16 v[100:103], v[226:229], v[180:183], v[100:103]
	v_mfma_f32_16x16x32_bf16 v[96:99], v[234:237], v[180:183], v[96:99]
	v_mfma_f32_16x16x32_bf16 v[84:87], v[226:229], v[188:191], v[84:87]
	v_mfma_f32_16x16x32_bf16 v[80:83], v[234:237], v[188:191], v[80:83]
	v_mfma_f32_16x16x32_bf16 v[68:71], v[226:229], v[196:199], v[68:71]
	v_mfma_f32_16x16x32_bf16 v[64:67], v[234:237], v[196:199], v[64:67]
	s_setprio 0
	s_barrier
	ds_read_b128 v[168:171], v212 offset:49152
	ds_read_b128 v[172:175], v212 offset:50176
	ds_read_b128 v[176:179], v212 offset:51200
	ds_read_b128 v[180:183], v212 offset:52224
	ds_read_b128 v[184:187], v212 offset:53248
	ds_read_b128 v[188:191], v212 offset:54272
	ds_read_b128 v[192:195], v212 offset:55296
	ds_read_b128 v[196:199], v212 offset:56320
	s_mov_b32 m0, s51
	v_lshl_add_u64 v[200:201], v[200:201], 0, s[18:19]
	global_load_lds_dwordx4 v[200:201], off
	v_lshl_add_u64 v[200:201], v[238:239], 0, s[18:19]
	s_mov_b32 m0, s52
	s_nop 0
	global_load_lds_dwordx4 v[200:201], off
	s_mov_b32 m0, s54
	v_lshl_add_u64 v[200:201], v[240:241], 0, s[18:19]
	global_load_lds_dwordx4 v[200:201], off
	v_lshl_add_u64 v[200:201], v[242:243], 0, s[18:19]
	s_mov_b32 m0, s55
	s_nop 0
	global_load_lds_dwordx4 v[200:201], off
	s_add_u32 s4, s4, 0x40080
	s_addc_u32 s5, s5, 0
	s_mov_b32 m0, s56
	v_lshl_add_u64 v[248:249], s[4:5], 0, v[144:145]
	global_load_lds_dwordx4 v[248:249], off
	v_lshl_add_u64 v[248:249], s[4:5], 0, v[146:147]
	s_mov_b32 m0, s57
	s_nop 0
	global_load_lds_dwordx4 v[248:249], off
	s_waitcnt lgkmcnt(0)
	s_waitcnt vmcnt(8)
	s_barrier
	s_setprio 1
	v_mfma_f32_16x16x32_bf16 v[60:63], v[128:131], v[168:171], v[60:63]
	v_mfma_f32_16x16x32_bf16 v[56:59], v[136:139], v[168:171], v[56:59]
	v_mfma_f32_16x16x32_bf16 v[44:47], v[128:131], v[176:179], v[44:47]
	v_mfma_f32_16x16x32_bf16 v[40:43], v[136:139], v[176:179], v[40:43]
	v_mfma_f32_16x16x32_bf16 v[28:31], v[128:131], v[184:187], v[28:31]
	v_mfma_f32_16x16x32_bf16 v[24:27], v[136:139], v[184:187], v[24:27]
	v_mfma_f32_16x16x32_bf16 v[12:15], v[128:131], v[192:195], v[12:15]
	v_mfma_f32_16x16x32_bf16 v[8:11], v[136:139], v[192:195], v[8:11]
	v_mfma_f32_16x16x32_bf16 v[60:63], v[132:135], v[172:175], v[60:63]
	v_mfma_f32_16x16x32_bf16 v[56:59], v[140:143], v[172:175], v[56:59]
	v_mfma_f32_16x16x32_bf16 v[44:47], v[132:135], v[180:183], v[44:47]
	v_mfma_f32_16x16x32_bf16 v[40:43], v[140:143], v[180:183], v[40:43]
	v_mfma_f32_16x16x32_bf16 v[28:31], v[132:135], v[188:191], v[28:31]
	v_mfma_f32_16x16x32_bf16 v[24:27], v[140:143], v[188:191], v[24:27]
	v_mfma_f32_16x16x32_bf16 v[12:15], v[132:135], v[196:199], v[12:15]
	v_mfma_f32_16x16x32_bf16 v[8:11], v[140:143], v[196:199], v[8:11]
	v_mfma_f32_16x16x32_bf16 v[52:55], v[222:225], v[168:171], v[52:55]
	v_mfma_f32_16x16x32_bf16 v[48:51], v[230:233], v[168:171], v[48:51]
	v_mfma_f32_16x16x32_bf16 v[36:39], v[222:225], v[176:179], v[36:39]
	v_mfma_f32_16x16x32_bf16 v[32:35], v[230:233], v[176:179], v[32:35]
	v_mfma_f32_16x16x32_bf16 v[20:23], v[222:225], v[184:187], v[20:23]
	v_mfma_f32_16x16x32_bf16 v[16:19], v[230:233], v[184:187], v[16:19]
	v_mfma_f32_16x16x32_bf16 v[4:7], v[222:225], v[192:195], v[4:7]
	v_mfma_f32_16x16x32_bf16 v[0:3], v[230:233], v[192:195], v[0:3]
	v_mfma_f32_16x16x32_bf16 v[52:55], v[226:229], v[172:175], v[52:55]
	v_mfma_f32_16x16x32_bf16 v[48:51], v[234:237], v[172:175], v[48:51]
	v_mfma_f32_16x16x32_bf16 v[36:39], v[226:229], v[180:183], v[36:39]
	v_mfma_f32_16x16x32_bf16 v[32:35], v[234:237], v[180:183], v[32:35]
	v_mfma_f32_16x16x32_bf16 v[20:23], v[226:229], v[188:191], v[20:23]
	v_mfma_f32_16x16x32_bf16 v[16:19], v[234:237], v[188:191], v[16:19]
	v_mfma_f32_16x16x32_bf16 v[4:7], v[226:229], v[196:199], v[4:7]
	v_mfma_f32_16x16x32_bf16 v[0:3], v[234:237], v[196:199], v[0:3]
	s_setprio 0
	s_add_i32 s69, s69, 2
	s_add_u32 s2, s2, 0x100
	s_addc_u32 s3, s3, 0
	s_add_u32 s38, s38, 0x100
	s_addc_u32 s39, s39, 0
	s_cmp_gt_u32 s69, 13
	s_barrier
